# E46: grid barrier - the last XCD leader no longer issues (and waits for) the now-unused release-generation add
# baseline (speedup 1.0000x reference)
; DI unsigned xb_ld(unsigned* p)              { return __hip_atomic_load(p, __ATOMIC_RELAXED, __HIP_MEMORY_SCOPE_AGENT); }
; DI unsigned xb_add(unsigned* p, unsigned v) { return __hip_atomic_fetch_add(p, v, __ATOMIC_RELAXED, __HIP_MEMORY_SCOPE_AGENT); }
; #define XB_SPIN(cond, bar) do { unsigned _sp = 0; while (cond) { __builtin_amdgcn_s_sleep(1); \
;     if ((++_sp & 255u) == 0u) { if (xb_ld(&(bar)[XB_TMO])) break; if (_sp > XB_SPIN_CAP) { atomicAdd(&(bar)[XB_TMO], 1u); break; } } } } while (0)
; DI void xcd_barrier(const XcdBarrier& b) {
;     ...
;         const unsigned old = xb_add(&bar[XB_XSUB(b.x)], 1u);
;         const unsigned gen = old / nloc;
;         if (old + 1u == (gen + 1u) * nloc) {
;             __builtin_amdgcn_fence(__ATOMIC_RELEASE, "agent");
;             asm volatile("s_waitcnt vmcnt(0)" ::: "memory");
;             const unsigned og = xb_add(&bar[XB_TOP], 1u);
;             const unsigned tg = og / nx;
;             if (og + 1u == (tg + 1u) * nx) xb_add(&bar[XB_TOPGEN], 1u);
;             else XB_SPIN(xb_ld(&bar[XB_TOPGEN]) == tg, bar);
;             __builtin_amdgcn_fence(__ATOMIC_ACQUIRE, "agent");
;             xb_add(&bar[XB_XGEN(b.x)], 1u);
;             asm volatile("s_waitcnt vmcnt(0)" ::: "memory");
.LBB0_75:
	s_or_b64 exec, exec, s[12:13]
	v_cvt_f32_u32_e32 v3, v0
	s_waitcnt vmcnt(0)
	v_readfirstlane_b32 s12, v2
	s_add_u32 s10, s36, 0x7500
	s_addc_u32 s11, s37, 0
	v_rcp_iflag_f32_e32 v3, v3
	v_add_u32_e32 v1, s12, v1
	s_mov_b64 s[14:15], 0
	v_mul_f32_e32 v2, 0x4f7ffffe, v3
	v_cvt_u32_f32_e32 v2, v2
	v_sub_u32_e32 v3, 0, v0
	v_mul_lo_u32 v3, v3, v2
	v_mul_hi_u32 v3, v2, v3
	v_add_u32_e32 v2, v2, v3
	v_mul_hi_u32 v2, v1, v2
	v_mul_lo_u32 v3, v2, v0
	v_sub_u32_e32 v3, v1, v3
	v_add_u32_e32 v4, 1, v2
	v_cmp_ge_u32_e32 vcc, v3, v0
	v_add_u32_e32 v1, 1, v1
	s_nop 0
	v_cndmask_b32_e32 v2, v2, v4, vcc
	v_sub_u32_e32 v4, v3, v0
	v_cndmask_b32_e32 v3, v3, v4, vcc
	v_add_u32_e32 v4, 1, v2
	v_cmp_ge_u32_e32 vcc, v3, v0
	s_nop 1
	v_cndmask_b32_e32 v2, v2, v4, vcc
	v_mul_lo_u32 v3, v0, v2
	v_add_u32_e32 v0, v3, v0
	v_cmp_ne_u32_e32 vcc, v1, v0
	v_mov_b32_e32 v2, v0
	v_mov_b64_e32 v[0:1], s[10:11]
	s_and_saveexec_b64 s[12:13], vcc
	s_cbranch_execz .LBB0_87
	s_sub_u32 s10, s10, 0x100
	s_subb_u32 s11, s11, 0
	v_mov_b32_e32 v0, 0
	global_load_dword v1, v0, s[10:11] sc1
	s_mov_b64 s[16:17], 0
	s_waitcnt vmcnt(0)
	v_cmp_lt_u32_e32 vcc, v1, v2
	s_and_saveexec_b64 s[14:15], vcc
	s_cbranch_execz .LBB0_86
	s_mov_b32 s26, 1
	s_branch .LBB0_79

; DI unsigned xb_ld(unsigned* p)              { return __hip_atomic_load(p, __ATOMIC_RELAXED, __HIP_MEMORY_SCOPE_AGENT); }
; DI unsigned xb_add(unsigned* p, unsigned v) { return __hip_atomic_fetch_add(p, v, __ATOMIC_RELAXED, __HIP_MEMORY_SCOPE_AGENT); }
; #define XB_SPIN(cond, bar) do { unsigned _sp = 0; while (cond) { __builtin_amdgcn_s_sleep(1); \
;     if ((++_sp & 255u) == 0u) { if (xb_ld(&(bar)[XB_TMO])) break; if (_sp > XB_SPIN_CAP) { atomicAdd(&(bar)[XB_TMO], 1u); break; } } } } while (0)
; DI void xcd_barrier(const XcdBarrier& b) {
;     ...
;         const unsigned old = xb_add(&bar[XB_XSUB(b.x)], 1u);
;         const unsigned gen = old / nloc;
;         if (old + 1u == (gen + 1u) * nloc) {
;             __builtin_amdgcn_fence(__ATOMIC_RELEASE, "agent");
;             asm volatile("s_waitcnt vmcnt(0)" ::: "memory");
;             const unsigned og = xb_add(&bar[XB_TOP], 1u);
;             const unsigned tg = og / nx;
;             if (og + 1u == (tg + 1u) * nx) xb_add(&bar[XB_TOPGEN], 1u);
;             else XB_SPIN(xb_ld(&bar[XB_TOPGEN]) == tg, bar);
;             __builtin_amdgcn_fence(__ATOMIC_ACQUIRE, "agent");
;             xb_add(&bar[XB_XGEN(b.x)], 1u);
;             asm volatile("s_waitcnt vmcnt(0)" ::: "memory");
.LBB0_1022:
	s_or_b64 exec, exec, s[6:7]
	s_waitcnt vmcnt(0)
	v_readfirstlane_b32 s4, v2
	v_cvt_f32_u32_e32 v2, v0
	v_sub_u32_e32 v3, 0, v0
	v_add_u32_e32 v1, s4, v1
	v_readlane_b32 s4, v253, 58
	v_rcp_iflag_f32_e32 v2, v2
	v_readlane_b32 s5, v253, 59
	s_mov_b64 s[6:7], 0
	v_mul_f32_e32 v2, 0x4f7ffffe, v2
	v_cvt_u32_f32_e32 v2, v2
	v_mul_lo_u32 v3, v3, v2
	v_mul_hi_u32 v3, v2, v3
	v_add_u32_e32 v2, v2, v3
	v_mul_hi_u32 v2, v1, v2
	v_mul_lo_u32 v3, v2, v0
	v_sub_u32_e32 v3, v1, v3
	v_cmp_ge_u32_e32 vcc, v3, v0
	v_add_u32_e32 v4, 1, v2
	v_add_u32_e32 v1, 1, v1
	v_cndmask_b32_e32 v2, v2, v4, vcc
	v_sub_u32_e32 v4, v3, v0
	v_cndmask_b32_e32 v3, v3, v4, vcc
	v_cmp_ge_u32_e32 vcc, v3, v0
	v_add_u32_e32 v3, 1, v2
	s_nop 0
	v_cndmask_b32_e32 v2, v2, v3, vcc
	v_mul_lo_u32 v3, v0, v2
	v_add_u32_e32 v0, v3, v0
	v_cmp_ne_u32_e32 vcc, v1, v0
	v_mov_b32_e32 v2, v0
	v_mov_b64_e32 v[0:1], s[4:5]
	s_and_saveexec_b64 s[4:5], vcc
	s_cbranch_execz .LBB0_1034
	v_readlane_b32 s6, v253, 56
	v_readlane_b32 s7, v253, 57
	s_mov_b64 s[8:9], 0
	s_nop 3
	global_load_dword v0, v173, s[6:7] sc1
	s_waitcnt vmcnt(0)
	v_cmp_lt_u32_e32 vcc, v0, v2
	s_and_saveexec_b64 s[6:7], vcc
	s_cbranch_execz .LBB0_1033
	s_mov_b32 s18, 1
	s_branch .LBB0_1026
